# last-layer down-proj epilogue fused with final RMSNorm (row-tile counters + partial sum exchange), final phase removed
# speedup vs baseline: 1.0073x; 1.0073x over previous
.LBB0_1322:
	s_cmp_lg_u32 s2, 0
	s_cbranch_scc1 .Lfz_zskip
	v_lshrrev_b32_e32 v211, 2, v176
	v_mov_b32_e32 v212, 0
	s_add_u32 s10, s54, 0xe0000
	s_addc_u32 s11, s55, 0
	global_store_dword v211, v212, s[10:11] sc1

.LBB0_1806:
	s_cmp_eq_u64 s[78:79], 0
	s_cbranch_scc1 .Lfz_start
	s_mul_i32 s18, s20, 9
	s_cmp_lg_u32 s95, s18
	s_cselect_b32 s18, s20, 4
	s_mul_hi_i32 s19, s18, 0xc000
	s_mul_i32 s18, s18, 0xc000
	s_add_u32 s18, s33, s18
	s_addc_u32 s19, s34, s19
	v_lshl_add_u64 v[130:131], s[18:19], 0, v[150:151]
	s_lshl_b32 s18, s95, 8
	s_add_i32 s18, s18, s35
	v_readlane_b32 s20, v253, 50
	v_add_u32_e32 v154, s18, v128
	v_readlane_b32 s21, v253, 51
	v_ashrrev_i32_e32 v155, 31, v154
	v_add_u32_e32 v178, 16, v154
	v_add_u32_e32 v194, 32, v154
	v_add_u32_e32 v210, 48, v154
	v_lshl_add_u64 v[152:153], s[20:21], 0, v[150:151]
	v_lshlrev_b64 v[224:225], 13, v[154:155]
	v_ashrrev_i32_e32 v179, 31, v178
	v_ashrrev_i32_e32 v195, 31, v194
	v_ashrrev_i32_e32 v211, 31, v210
	v_lshl_add_u64 v[172:173], v[152:153], 0, v[224:225]
	v_lshlrev_b64 v[228:229], 13, v[178:179]
	v_lshlrev_b64 v[246:247], 13, v[194:195]
	v_lshlrev_b64 v[248:249], 13, v[210:211]
	global_load_dwordx4 v[160:163], v[172:173], off
	global_load_dwordx4 v[140:143], v[130:131], off
	global_load_dwordx4 v[136:139], v[130:131], off offset:64
	global_load_dwordx4 v[164:167], v[172:173], off offset:64
	global_load_dwordx4 v[168:171], v[172:173], off offset:512
	global_load_dwordx4 v[132:135], v[130:131], off offset:512
	s_nop 0
	global_load_dwordx4 v[128:131], v[130:131], off offset:576
	s_nop 0
	global_load_dwordx4 v[172:175], v[172:173], off offset:576
	v_lshl_add_u64 v[190:191], v[152:153], 0, v[228:229]
	v_lshl_add_u64 v[206:207], v[152:153], 0, v[246:247]
	v_lshl_add_u64 v[242:243], v[152:153], 0, v[248:249]
	global_load_dwordx4 v[178:181], v[190:191], off
	global_load_dwordx4 v[182:185], v[190:191], off offset:64
	global_load_dwordx4 v[186:189], v[190:191], off offset:512
	s_nop 0
	global_load_dwordx4 v[190:193], v[190:191], off offset:576
	s_nop 0
	global_load_dwordx4 v[194:197], v[206:207], off
	global_load_dwordx4 v[198:201], v[206:207], off offset:64
	global_load_dwordx4 v[202:205], v[206:207], off offset:512
	s_nop 0
	global_load_dwordx4 v[206:209], v[206:207], off offset:576
	s_nop 0
	global_load_dwordx4 v[210:213], v[242:243], off
	global_load_dwordx4 v[220:223], v[242:243], off offset:64
	global_load_dwordx4 v[238:241], v[242:243], off offset:512
	s_nop 0
	global_load_dwordx4 v[242:245], v[242:243], off offset:576
	v_lshl_add_u64 v[224:225], s[20:21], 0, v[224:225]
	v_lshl_add_u64 v[224:225], v[224:225], 0, v[150:151]
	v_lshl_add_u64 v[228:229], s[20:21], 0, v[228:229]
	v_lshl_add_u64 v[248:249], s[20:21], 0, v[248:249]
	v_lshl_add_u64 v[246:247], s[20:21], 0, v[246:247]
	v_lshl_add_u64 v[228:229], v[228:229], 0, v[150:151]
	v_lshl_add_u64 v[248:249], v[248:249], 0, v[150:151]
	v_lshl_add_u64 v[246:247], v[246:247], 0, v[150:151]
	s_waitcnt vmcnt(0)
	v_pk_fma_f32 v[126:127], v[126:127], v[142:143], v[162:163]
	v_pk_fma_f32 v[124:125], v[124:125], v[140:141], v[160:161]
	v_pk_fma_f32 v[122:123], v[122:123], v[138:139], v[166:167]
	v_pk_fma_f32 v[120:121], v[120:121], v[136:137], v[164:165]
	v_pk_fma_f32 v[106:107], v[106:107], v[134:135], v[170:171]
	v_pk_fma_f32 v[104:105], v[104:105], v[132:133], v[168:169]
	v_pk_fma_f32 v[98:99], v[98:99], v[130:131], v[174:175]
	v_pk_fma_f32 v[96:97], v[96:97], v[128:129], v[172:173]
	global_store_dwordx4 v[224:225], v[124:127], off sc1
	global_store_dwordx4 v[224:225], v[120:123], off offset:64 sc1
	global_store_dwordx4 v[224:225], v[104:107], off offset:512 sc1
	global_store_dwordx4 v[224:225], v[96:99], off offset:576 sc1
	v_pk_fma_f32 v[90:91], v[90:91], v[134:135], v[188:189]
	v_pk_fma_f32 v[80:81], v[80:81], v[132:133], v[202:203]
	v_pk_fma_f32 v[98:99], v[118:119], v[142:143], v[180:181]
	v_pk_fma_f32 v[96:97], v[116:117], v[140:141], v[178:179]
	v_pk_fma_f32 v[66:67], v[66:67], v[130:131], v[244:245]
	v_pk_fma_f32 v[64:65], v[64:65], v[128:129], v[242:243]
	v_pk_fma_f32 v[106:107], v[114:115], v[138:139], v[184:185]
	v_pk_fma_f32 v[104:105], v[112:113], v[136:137], v[182:183]
	v_pk_fma_f32 v[88:89], v[88:89], v[132:133], v[186:187]
	v_pk_fma_f32 v[86:87], v[86:87], v[130:131], v[192:193]
	v_pk_fma_f32 v[84:85], v[84:85], v[128:129], v[190:191]
	v_pk_fma_f32 v[110:111], v[110:111], v[142:143], v[196:197]
	v_pk_fma_f32 v[108:109], v[108:109], v[140:141], v[194:195]
	v_pk_fma_f32 v[102:103], v[102:103], v[138:139], v[200:201]
	v_pk_fma_f32 v[100:101], v[100:101], v[136:137], v[198:199]
	v_pk_fma_f32 v[82:83], v[82:83], v[134:135], v[204:205]
	v_pk_fma_f32 v[78:79], v[78:79], v[130:131], v[208:209]
	v_pk_fma_f32 v[76:77], v[76:77], v[128:129], v[206:207]
	v_pk_fma_f32 v[94:95], v[94:95], v[142:143], v[212:213]
	v_pk_fma_f32 v[92:93], v[92:93], v[140:141], v[210:211]
	global_store_dwordx4 v[228:229], v[96:99], off sc1
	global_store_dwordx4 v[228:229], v[104:107], off offset:64 sc1
	global_store_dwordx4 v[228:229], v[88:91], off offset:512 sc1
	global_store_dwordx4 v[228:229], v[84:87], off offset:576 sc1
	global_store_dwordx4 v[246:247], v[108:111], off sc1
	global_store_dwordx4 v[246:247], v[100:103], off offset:64 sc1
	global_store_dwordx4 v[246:247], v[80:83], off offset:512 sc1
	global_store_dwordx4 v[246:247], v[76:79], off offset:576 sc1
	global_store_dwordx4 v[248:249], v[92:95], off sc1
	global_store_dwordx4 v[248:249], v[64:67], off offset:576 sc1
	v_add_u32_e32 v80, 0x90, v154
	v_add_u32_e32 v96, 0xa0, v154
	v_add_u32_e32 v64, 0x80, v154
	v_pk_fma_f32 v[74:75], v[74:75], v[138:139], v[222:223]
	v_pk_fma_f32 v[72:73], v[72:73], v[136:137], v[220:221]
	v_pk_fma_f32 v[70:71], v[70:71], v[134:135], v[240:241]
	v_pk_fma_f32 v[68:69], v[68:69], v[132:133], v[238:239]
	v_ashrrev_i32_e32 v65, 31, v64
	v_ashrrev_i32_e32 v81, 31, v80
	v_ashrrev_i32_e32 v97, 31, v96
	global_store_dwordx4 v[248:249], v[72:75], off offset:64 sc1
	global_store_dwordx4 v[248:249], v[68:71], off offset:512 sc1
	v_lshlrev_b64 v[160:161], 13, v[64:65]
	v_lshlrev_b64 v[162:163], 13, v[80:81]
	v_lshlrev_b64 v[164:165], 13, v[96:97]
	v_add_u32_e32 v112, 0xb0, v154
	v_lshl_add_u64 v[76:77], v[152:153], 0, v[160:161]
	v_lshl_add_u64 v[92:93], v[152:153], 0, v[162:163]
	v_lshl_add_u64 v[108:109], v[152:153], 0, v[164:165]
	v_ashrrev_i32_e32 v113, 31, v112
	global_load_dwordx4 v[64:67], v[76:77], off
	global_load_dwordx4 v[68:71], v[76:77], off offset:64
	global_load_dwordx4 v[72:75], v[76:77], off offset:512
	s_nop 0
	global_load_dwordx4 v[76:79], v[76:77], off offset:576
	s_nop 0
	global_load_dwordx4 v[80:83], v[92:93], off
	global_load_dwordx4 v[84:87], v[92:93], off offset:64
	global_load_dwordx4 v[88:91], v[92:93], off offset:512
	s_nop 0
	global_load_dwordx4 v[92:95], v[92:93], off offset:576
	s_nop 0
	global_load_dwordx4 v[96:99], v[108:109], off
	global_load_dwordx4 v[100:103], v[108:109], off offset:64
	global_load_dwordx4 v[104:107], v[108:109], off offset:512
	s_nop 0
	global_load_dwordx4 v[108:111], v[108:109], off offset:576
	v_lshlrev_b64 v[154:155], 13, v[112:113]
	v_lshl_add_u64 v[124:125], v[152:153], 0, v[154:155]
	global_load_dwordx4 v[112:115], v[124:125], off
	global_load_dwordx4 v[116:119], v[124:125], off offset:64
	global_load_dwordx4 v[120:123], v[124:125], off offset:512
	s_nop 0
	global_load_dwordx4 v[124:127], v[124:125], off offset:576
	v_lshl_add_u64 v[152:153], s[20:21], 0, v[160:161]
	v_lshl_add_u64 v[160:161], s[20:21], 0, v[162:163]
	v_lshl_add_u64 v[162:163], s[20:21], 0, v[164:165]
	v_lshl_add_u64 v[152:153], v[152:153], 0, v[150:151]
	v_lshl_add_u64 v[162:163], v[162:163], 0, v[150:151]
	v_lshl_add_u64 v[160:161], v[160:161], 0, v[150:151]
	s_waitcnt vmcnt(15)
	v_pk_fma_f32 v[62:63], v[62:63], v[142:143], v[66:67]
	v_pk_fma_f32 v[60:61], v[60:61], v[140:141], v[64:65]
	s_waitcnt vmcnt(14)
	v_pk_fma_f32 v[58:59], v[58:59], v[138:139], v[70:71]
	v_pk_fma_f32 v[56:57], v[56:57], v[136:137], v[68:69]
	s_waitcnt vmcnt(13)
	v_pk_fma_f32 v[42:43], v[42:43], v[134:135], v[74:75]
	s_waitcnt vmcnt(4)
	v_pk_fma_f32 v[14:15], v[14:15], v[130:131], v[110:111]
	v_pk_fma_f32 v[12:13], v[12:13], v[128:129], v[108:109]
	v_pk_fma_f32 v[40:41], v[40:41], v[132:133], v[72:73]
	v_pk_fma_f32 v[38:39], v[38:39], v[130:131], v[78:79]
	v_pk_fma_f32 v[36:37], v[36:37], v[128:129], v[76:77]
	v_pk_fma_f32 v[54:55], v[54:55], v[142:143], v[82:83]
	v_pk_fma_f32 v[52:53], v[52:53], v[140:141], v[80:81]
	v_pk_fma_f32 v[50:51], v[50:51], v[138:139], v[86:87]
	v_pk_fma_f32 v[48:49], v[48:49], v[136:137], v[84:85]
	v_pk_fma_f32 v[30:31], v[30:31], v[134:135], v[90:91]
	v_pk_fma_f32 v[28:29], v[28:29], v[132:133], v[88:89]
	v_pk_fma_f32 v[26:27], v[26:27], v[130:131], v[94:95]
	v_pk_fma_f32 v[24:25], v[24:25], v[128:129], v[92:93]
	v_pk_fma_f32 v[46:47], v[46:47], v[142:143], v[98:99]
	v_pk_fma_f32 v[44:45], v[44:45], v[140:141], v[96:97]
	v_pk_fma_f32 v[34:35], v[34:35], v[138:139], v[102:103]
	v_pk_fma_f32 v[32:33], v[32:33], v[136:137], v[100:101]
	v_pk_fma_f32 v[22:23], v[22:23], v[134:135], v[106:107]
	v_pk_fma_f32 v[20:21], v[20:21], v[132:133], v[104:105]
	global_store_dwordx4 v[152:153], v[60:63], off sc1
	global_store_dwordx4 v[152:153], v[56:59], off offset:64 sc1
	global_store_dwordx4 v[152:153], v[40:43], off offset:512 sc1
	global_store_dwordx4 v[152:153], v[36:39], off offset:576 sc1
	global_store_dwordx4 v[160:161], v[52:55], off sc1
	global_store_dwordx4 v[160:161], v[48:51], off offset:64 sc1
	global_store_dwordx4 v[160:161], v[28:31], off offset:512 sc1
	global_store_dwordx4 v[160:161], v[24:27], off offset:576 sc1
	global_store_dwordx4 v[162:163], v[44:47], off sc1
	global_store_dwordx4 v[162:163], v[32:35], off offset:64 sc1
	global_store_dwordx4 v[162:163], v[20:23], off offset:512 sc1
	global_store_dwordx4 v[162:163], v[12:15], off offset:576 sc1
	s_waitcnt vmcnt(14)
	v_pk_fma_f32 v[10:11], v[10:11], v[138:139], v[118:119]
	v_pk_fma_f32 v[8:9], v[8:9], v[136:137], v[116:117]
	v_lshl_add_u64 v[12:13], s[20:21], 0, v[154:155]
	v_lshl_add_u64 v[20:21], v[12:13], 0, v[150:151]
	v_pk_fma_f32 v[14:15], v[18:19], v[142:143], v[114:115]
	v_pk_fma_f32 v[12:13], v[16:17], v[140:141], v[112:113]
	s_waitcnt vmcnt(13)
	v_pk_fma_f32 v[6:7], v[6:7], v[134:135], v[122:123]
	v_pk_fma_f32 v[4:5], v[4:5], v[132:133], v[120:121]
	s_waitcnt vmcnt(12)
	v_pk_fma_f32 v[2:3], v[2:3], v[130:131], v[126:127]
	v_pk_fma_f32 v[0:1], v[0:1], v[128:129], v[124:125]
	global_store_dwordx4 v[20:21], v[12:15], off sc1
	global_store_dwordx4 v[20:21], v[8:11], off offset:64 sc1
	global_store_dwordx4 v[20:21], v[4:7], off offset:512 sc1
	global_store_dwordx4 v[20:21], v[0:3], off offset:576 sc1

.Lfz_start:
	v_mov_b32_e32 v153, v150
	s_lshl_b32 s18, s95, 8
	s_add_i32 s18, s18, s35
	v_add_u32_e32 v152, s18, v128
	s_mul_i32 s18, s20, 0xc000
	s_add_u32 s18, s33, s18
	s_addc_u32 s19, s34, 0
	global_load_dwordx4 v[132:135], v153, s[18:19] offset:0
	global_load_dwordx4 v[136:139], v153, s[18:19] offset:64
	global_load_dwordx4 v[140:143], v153, s[18:19] offset:512
	global_load_dwordx4 v[244:247], v153, s[18:19] offset:576
	v_readlane_b32 s100, v253, 50
	v_readlane_b32 s101, v253, 51
	s_add_u32 s100, s100, 0
	s_addc_u32 s101, s101, 0
	v_add_u32_e32 v154, 0, v152
	v_lshl_add_u32 v154, v154, 13, v153
	global_load_dwordx4 v[160:163], v154, s[100:101] offset:0
	global_load_dwordx4 v[164:167], v154, s[100:101] offset:64
	global_load_dwordx4 v[168:171], v154, s[100:101] offset:512
	global_load_dwordx4 v[172:175], v154, s[100:101] offset:576
	v_add_u32_e32 v154, 16, v152
	v_lshl_add_u32 v154, v154, 13, v153
	global_load_dwordx4 v[180:183], v154, s[100:101] offset:0
	global_load_dwordx4 v[184:187], v154, s[100:101] offset:64
	global_load_dwordx4 v[188:191], v154, s[100:101] offset:512
	global_load_dwordx4 v[192:195], v154, s[100:101] offset:576
	v_add_u32_e32 v154, 32, v152
	v_lshl_add_u32 v154, v154, 13, v153
	global_load_dwordx4 v[196:199], v154, s[100:101] offset:0
	global_load_dwordx4 v[200:203], v154, s[100:101] offset:64
	global_load_dwordx4 v[204:207], v154, s[100:101] offset:512
	global_load_dwordx4 v[208:211], v154, s[100:101] offset:576
	v_add_u32_e32 v154, 48, v152
	v_lshl_add_u32 v154, v154, 13, v153
	global_load_dwordx4 v[220:223], v154, s[100:101] offset:0
	global_load_dwordx4 v[232:235], v154, s[100:101] offset:64
	global_load_dwordx4 v[236:239], v154, s[100:101] offset:512
	global_load_dwordx4 v[240:243], v154, s[100:101] offset:576
	s_waitcnt vmcnt(0)
	v_pk_fma_f32 v[124:125], v[124:125], v[132:133], v[160:161]
	v_pk_fma_f32 v[126:127], v[126:127], v[134:135], v[162:163]
	v_pk_fma_f32 v[120:121], v[120:121], v[136:137], v[164:165]
	v_pk_fma_f32 v[122:123], v[122:123], v[138:139], v[166:167]
	v_pk_fma_f32 v[104:105], v[104:105], v[140:141], v[168:169]
	v_pk_fma_f32 v[106:107], v[106:107], v[142:143], v[170:171]
	v_pk_fma_f32 v[96:97], v[96:97], v[244:245], v[172:173]
	v_pk_fma_f32 v[98:99], v[98:99], v[246:247], v[174:175]
	v_pk_fma_f32 v[116:117], v[116:117], v[132:133], v[180:181]
	v_pk_fma_f32 v[118:119], v[118:119], v[134:135], v[182:183]
	v_pk_fma_f32 v[112:113], v[112:113], v[136:137], v[184:185]
	v_pk_fma_f32 v[114:115], v[114:115], v[138:139], v[186:187]
	v_pk_fma_f32 v[88:89], v[88:89], v[140:141], v[188:189]
	v_pk_fma_f32 v[90:91], v[90:91], v[142:143], v[190:191]
	v_pk_fma_f32 v[84:85], v[84:85], v[244:245], v[192:193]
	v_pk_fma_f32 v[86:87], v[86:87], v[246:247], v[194:195]
	v_pk_fma_f32 v[108:109], v[108:109], v[132:133], v[196:197]
	v_pk_fma_f32 v[110:111], v[110:111], v[134:135], v[198:199]
	v_pk_fma_f32 v[100:101], v[100:101], v[136:137], v[200:201]
	v_pk_fma_f32 v[102:103], v[102:103], v[138:139], v[202:203]
	v_pk_fma_f32 v[80:81], v[80:81], v[140:141], v[204:205]
	v_pk_fma_f32 v[82:83], v[82:83], v[142:143], v[206:207]
	v_pk_fma_f32 v[76:77], v[76:77], v[244:245], v[208:209]
	v_pk_fma_f32 v[78:79], v[78:79], v[246:247], v[210:211]
	v_pk_fma_f32 v[92:93], v[92:93], v[132:133], v[220:221]
	v_pk_fma_f32 v[94:95], v[94:95], v[134:135], v[222:223]
	v_pk_fma_f32 v[72:73], v[72:73], v[136:137], v[232:233]
	v_pk_fma_f32 v[74:75], v[74:75], v[138:139], v[234:235]
	v_pk_fma_f32 v[68:69], v[68:69], v[140:141], v[236:237]
	v_pk_fma_f32 v[70:71], v[70:71], v[142:143], v[238:239]
	v_pk_fma_f32 v[64:65], v[64:65], v[244:245], v[240:241]
	v_pk_fma_f32 v[66:67], v[66:67], v[246:247], v[242:243]
	v_add_u32_e32 v154, 128, v152
	v_lshl_add_u32 v154, v154, 13, v153
	global_load_dwordx4 v[160:163], v154, s[100:101] offset:0
	global_load_dwordx4 v[164:167], v154, s[100:101] offset:64
	global_load_dwordx4 v[168:171], v154, s[100:101] offset:512
	global_load_dwordx4 v[172:175], v154, s[100:101] offset:576
	v_add_u32_e32 v154, 144, v152
	v_lshl_add_u32 v154, v154, 13, v153
	global_load_dwordx4 v[180:183], v154, s[100:101] offset:0
	global_load_dwordx4 v[184:187], v154, s[100:101] offset:64
	global_load_dwordx4 v[188:191], v154, s[100:101] offset:512
	global_load_dwordx4 v[192:195], v154, s[100:101] offset:576
	v_add_u32_e32 v154, 160, v152
	v_lshl_add_u32 v154, v154, 13, v153
	global_load_dwordx4 v[196:199], v154, s[100:101] offset:0
	global_load_dwordx4 v[200:203], v154, s[100:101] offset:64
	global_load_dwordx4 v[204:207], v154, s[100:101] offset:512
	global_load_dwordx4 v[208:211], v154, s[100:101] offset:576
	v_add_u32_e32 v154, 176, v152
	v_lshl_add_u32 v154, v154, 13, v153
	global_load_dwordx4 v[220:223], v154, s[100:101] offset:0
	global_load_dwordx4 v[232:235], v154, s[100:101] offset:64
	global_load_dwordx4 v[236:239], v154, s[100:101] offset:512
	global_load_dwordx4 v[240:243], v154, s[100:101] offset:576
	s_waitcnt vmcnt(0)
	v_pk_fma_f32 v[60:61], v[60:61], v[132:133], v[160:161]
	v_pk_fma_f32 v[62:63], v[62:63], v[134:135], v[162:163]
	v_pk_fma_f32 v[56:57], v[56:57], v[136:137], v[164:165]
	v_pk_fma_f32 v[58:59], v[58:59], v[138:139], v[166:167]
	v_pk_fma_f32 v[40:41], v[40:41], v[140:141], v[168:169]
	v_pk_fma_f32 v[42:43], v[42:43], v[142:143], v[170:171]
	v_pk_fma_f32 v[36:37], v[36:37], v[244:245], v[172:173]
	v_pk_fma_f32 v[38:39], v[38:39], v[246:247], v[174:175]
	v_pk_fma_f32 v[52:53], v[52:53], v[132:133], v[180:181]
	v_pk_fma_f32 v[54:55], v[54:55], v[134:135], v[182:183]
	v_pk_fma_f32 v[48:49], v[48:49], v[136:137], v[184:185]
	v_pk_fma_f32 v[50:51], v[50:51], v[138:139], v[186:187]
	v_pk_fma_f32 v[28:29], v[28:29], v[140:141], v[188:189]
	v_pk_fma_f32 v[30:31], v[30:31], v[142:143], v[190:191]
	v_pk_fma_f32 v[24:25], v[24:25], v[244:245], v[192:193]
	v_pk_fma_f32 v[26:27], v[26:27], v[246:247], v[194:195]
	v_pk_fma_f32 v[44:45], v[44:45], v[132:133], v[196:197]
	v_pk_fma_f32 v[46:47], v[46:47], v[134:135], v[198:199]
	v_pk_fma_f32 v[32:33], v[32:33], v[136:137], v[200:201]
	v_pk_fma_f32 v[34:35], v[34:35], v[138:139], v[202:203]
	v_pk_fma_f32 v[20:21], v[20:21], v[140:141], v[204:205]
	v_pk_fma_f32 v[22:23], v[22:23], v[142:143], v[206:207]
	v_pk_fma_f32 v[12:13], v[12:13], v[244:245], v[208:209]
	v_pk_fma_f32 v[14:15], v[14:15], v[246:247], v[210:211]
	v_pk_fma_f32 v[16:17], v[16:17], v[132:133], v[220:221]
	v_pk_fma_f32 v[18:19], v[18:19], v[134:135], v[222:223]
	v_pk_fma_f32 v[8:9], v[8:9], v[136:137], v[232:233]
	v_pk_fma_f32 v[10:11], v[10:11], v[138:139], v[234:235]
	v_pk_fma_f32 v[4:5], v[4:5], v[140:141], v[236:237]
	v_pk_fma_f32 v[6:7], v[6:7], v[142:143], v[238:239]
	v_pk_fma_f32 v[0:1], v[0:1], v[244:245], v[240:241]
	v_pk_fma_f32 v[2:3], v[2:3], v[246:247], v[242:243]
	v_mul_f32_e32 v160, v124, v124
	v_fmac_f32_e32 v160, v125, v125
	v_fmac_f32_e32 v160, v126, v126
	v_fmac_f32_e32 v160, v127, v127
	v_fmac_f32_e32 v160, v120, v120
	v_fmac_f32_e32 v160, v121, v121
	v_fmac_f32_e32 v160, v122, v122
	v_fmac_f32_e32 v160, v123, v123
	v_fmac_f32_e32 v160, v104, v104
	v_fmac_f32_e32 v160, v105, v105
	v_fmac_f32_e32 v160, v106, v106
	v_fmac_f32_e32 v160, v107, v107
	v_fmac_f32_e32 v160, v96, v96
	v_fmac_f32_e32 v160, v97, v97
	v_fmac_f32_e32 v160, v98, v98
	v_fmac_f32_e32 v160, v99, v99
	v_mul_f32_e32 v161, v116, v116
	v_fmac_f32_e32 v161, v117, v117
	v_fmac_f32_e32 v161, v118, v118
	v_fmac_f32_e32 v161, v119, v119
	v_fmac_f32_e32 v161, v112, v112
	v_fmac_f32_e32 v161, v113, v113
	v_fmac_f32_e32 v161, v114, v114
	v_fmac_f32_e32 v161, v115, v115
	v_fmac_f32_e32 v161, v88, v88
	v_fmac_f32_e32 v161, v89, v89
	v_fmac_f32_e32 v161, v90, v90
	v_fmac_f32_e32 v161, v91, v91
	v_fmac_f32_e32 v161, v84, v84
	v_fmac_f32_e32 v161, v85, v85
	v_fmac_f32_e32 v161, v86, v86
	v_fmac_f32_e32 v161, v87, v87
	v_mul_f32_e32 v162, v108, v108
	v_fmac_f32_e32 v162, v109, v109
	v_fmac_f32_e32 v162, v110, v110
	v_fmac_f32_e32 v162, v111, v111
	v_fmac_f32_e32 v162, v100, v100
	v_fmac_f32_e32 v162, v101, v101
	v_fmac_f32_e32 v162, v102, v102
	v_fmac_f32_e32 v162, v103, v103
	v_fmac_f32_e32 v162, v80, v80
	v_fmac_f32_e32 v162, v81, v81
	v_fmac_f32_e32 v162, v82, v82
	v_fmac_f32_e32 v162, v83, v83
	v_fmac_f32_e32 v162, v76, v76
	v_fmac_f32_e32 v162, v77, v77
	v_fmac_f32_e32 v162, v78, v78
	v_fmac_f32_e32 v162, v79, v79
	v_mul_f32_e32 v163, v92, v92
	v_fmac_f32_e32 v163, v93, v93
	v_fmac_f32_e32 v163, v94, v94
	v_fmac_f32_e32 v163, v95, v95
	v_fmac_f32_e32 v163, v72, v72
	v_fmac_f32_e32 v163, v73, v73
	v_fmac_f32_e32 v163, v74, v74
	v_fmac_f32_e32 v163, v75, v75
	v_fmac_f32_e32 v163, v68, v68
	v_fmac_f32_e32 v163, v69, v69
	v_fmac_f32_e32 v163, v70, v70
	v_fmac_f32_e32 v163, v71, v71
	v_fmac_f32_e32 v163, v64, v64
	v_fmac_f32_e32 v163, v65, v65
	v_fmac_f32_e32 v163, v66, v66
	v_fmac_f32_e32 v163, v67, v67
	v_mul_f32_e32 v164, v60, v60
	v_fmac_f32_e32 v164, v61, v61
	v_fmac_f32_e32 v164, v62, v62
	v_fmac_f32_e32 v164, v63, v63
	v_fmac_f32_e32 v164, v56, v56
	v_fmac_f32_e32 v164, v57, v57
	v_fmac_f32_e32 v164, v58, v58
	v_fmac_f32_e32 v164, v59, v59
	v_fmac_f32_e32 v164, v40, v40
	v_fmac_f32_e32 v164, v41, v41
	v_fmac_f32_e32 v164, v42, v42
	v_fmac_f32_e32 v164, v43, v43
	v_fmac_f32_e32 v164, v36, v36
	v_fmac_f32_e32 v164, v37, v37
	v_fmac_f32_e32 v164, v38, v38
	v_fmac_f32_e32 v164, v39, v39
	v_mul_f32_e32 v165, v52, v52
	v_fmac_f32_e32 v165, v53, v53
	v_fmac_f32_e32 v165, v54, v54
	v_fmac_f32_e32 v165, v55, v55
	v_fmac_f32_e32 v165, v48, v48
	v_fmac_f32_e32 v165, v49, v49
	v_fmac_f32_e32 v165, v50, v50
	v_fmac_f32_e32 v165, v51, v51
	v_fmac_f32_e32 v165, v28, v28
	v_fmac_f32_e32 v165, v29, v29
	v_fmac_f32_e32 v165, v30, v30
	v_fmac_f32_e32 v165, v31, v31
	v_fmac_f32_e32 v165, v24, v24
	v_fmac_f32_e32 v165, v25, v25
	v_fmac_f32_e32 v165, v26, v26
	v_fmac_f32_e32 v165, v27, v27
	v_mul_f32_e32 v166, v44, v44
	v_fmac_f32_e32 v166, v45, v45
	v_fmac_f32_e32 v166, v46, v46
	v_fmac_f32_e32 v166, v47, v47
	v_fmac_f32_e32 v166, v32, v32
	v_fmac_f32_e32 v166, v33, v33
	v_fmac_f32_e32 v166, v34, v34
	v_fmac_f32_e32 v166, v35, v35
	v_fmac_f32_e32 v166, v20, v20
	v_fmac_f32_e32 v166, v21, v21
	v_fmac_f32_e32 v166, v22, v22
	v_fmac_f32_e32 v166, v23, v23
	v_fmac_f32_e32 v166, v12, v12
	v_fmac_f32_e32 v166, v13, v13
	v_fmac_f32_e32 v166, v14, v14
	v_fmac_f32_e32 v166, v15, v15
	v_mul_f32_e32 v167, v16, v16
	v_fmac_f32_e32 v167, v17, v17
	v_fmac_f32_e32 v167, v18, v18
	v_fmac_f32_e32 v167, v19, v19
	v_fmac_f32_e32 v167, v8, v8
	v_fmac_f32_e32 v167, v9, v9
	v_fmac_f32_e32 v167, v10, v10
	v_fmac_f32_e32 v167, v11, v11
	v_fmac_f32_e32 v167, v4, v4
	v_fmac_f32_e32 v167, v5, v5
	v_fmac_f32_e32 v167, v6, v6
	v_fmac_f32_e32 v167, v7, v7
	v_fmac_f32_e32 v167, v0, v0
	v_fmac_f32_e32 v167, v1, v1
	v_fmac_f32_e32 v167, v2, v2
	v_fmac_f32_e32 v167, v3, v3
	v_mov_b32_e32 v168, v160
	v_mov_b32_e32 v169, v161
	v_mov_b32_e32 v170, v162
	v_mov_b32_e32 v171, v163
	v_mov_b32_e32 v172, v164
	v_mov_b32_e32 v173, v165
	v_mov_b32_e32 v174, v166
	v_mov_b32_e32 v175, v167
	s_nop 1
	v_permlane32_swap_b32_e32 v160, v168
	v_permlane32_swap_b32_e32 v161, v169
	v_permlane32_swap_b32_e32 v162, v170
	v_permlane32_swap_b32_e32 v163, v171
	v_permlane32_swap_b32_e32 v164, v172
	v_permlane32_swap_b32_e32 v165, v173
	v_permlane32_swap_b32_e32 v166, v174
	v_permlane32_swap_b32_e32 v167, v175
	s_nop 1
	v_add_f32_e32 v160, v160, v168
	v_add_f32_e32 v161, v161, v169
	v_add_f32_e32 v162, v162, v170
	v_add_f32_e32 v163, v163, v171
	v_add_f32_e32 v164, v164, v172
	v_add_f32_e32 v165, v165, v173
	v_add_f32_e32 v166, v166, v174
	v_add_f32_e32 v167, v167, v175
	v_mov_b32_e32 v168, v160
	v_mov_b32_e32 v169, v161
	v_mov_b32_e32 v170, v162
	v_mov_b32_e32 v171, v163
	v_mov_b32_e32 v172, v164
	v_mov_b32_e32 v173, v165
	v_mov_b32_e32 v174, v166
	v_mov_b32_e32 v175, v167
	s_nop 1
	v_permlane16_swap_b32_e32 v160, v168
	v_permlane16_swap_b32_e32 v161, v169
	v_permlane16_swap_b32_e32 v162, v170
	v_permlane16_swap_b32_e32 v163, v171
	v_permlane16_swap_b32_e32 v164, v172
	v_permlane16_swap_b32_e32 v165, v173
	v_permlane16_swap_b32_e32 v166, v174
	v_permlane16_swap_b32_e32 v167, v175
	s_nop 1
	v_add_f32_e32 v160, v160, v168
	v_add_f32_e32 v161, v161, v169
	v_add_f32_e32 v162, v162, v170
	v_add_f32_e32 v163, v163, v171
	v_add_f32_e32 v164, v164, v172
	v_add_f32_e32 v165, v165, v173
	v_add_f32_e32 v166, v166, v174
	v_add_f32_e32 v167, v167, v175
	s_lshr_b32 s18, s35, 6
	s_lshl_b32 s18, s18, 2
	s_lshr_b32 s19, s36, 5
	s_add_i32 s18, s18, s19
	s_lshl_b32 s18, s18, 9
	s_add_i32 s18, s18, 0x20000
	v_lshl_add_u32 v154, v128, 2, s18
	ds_write_b32 v154, v160 offset:0
	ds_write_b32 v154, v161 offset:64
	ds_write_b32 v154, v162 offset:128
	ds_write_b32 v154, v163 offset:192
	ds_write_b32 v154, v164 offset:256
	ds_write_b32 v154, v165 offset:320
	ds_write_b32 v154, v166 offset:384
	ds_write_b32 v154, v167 offset:448
	s_waitcnt lgkmcnt(0)
	s_barrier
	s_lshr_b32 s18, s35, 6
	s_lshl_b32 s18, s18, 11
	s_add_i32 s18, s18, 0x20000
	v_lshl_add_u32 v154, v128, 2, s18
	ds_read_b32 v180, v154 offset:0
	ds_read_b32 v181, v154 offset:512
	ds_read_b32 v182, v154 offset:1024
	ds_read_b32 v183, v154 offset:1536
	ds_read_b32 v184, v154 offset:64
	ds_read_b32 v185, v154 offset:576
	ds_read_b32 v186, v154 offset:1088
	ds_read_b32 v187, v154 offset:1600
	ds_read_b32 v188, v154 offset:128
	ds_read_b32 v189, v154 offset:640
	ds_read_b32 v190, v154 offset:1152
	ds_read_b32 v191, v154 offset:1664
	ds_read_b32 v192, v154 offset:192
	ds_read_b32 v193, v154 offset:704
	ds_read_b32 v194, v154 offset:1216
	ds_read_b32 v195, v154 offset:1728
	ds_read_b32 v196, v154 offset:256
	ds_read_b32 v197, v154 offset:768
	ds_read_b32 v198, v154 offset:1280
	ds_read_b32 v199, v154 offset:1792
	ds_read_b32 v200, v154 offset:320
	ds_read_b32 v201, v154 offset:832
	ds_read_b32 v202, v154 offset:1344
	ds_read_b32 v203, v154 offset:1856
	ds_read_b32 v204, v154 offset:384
	ds_read_b32 v205, v154 offset:896
	ds_read_b32 v206, v154 offset:1408
	ds_read_b32 v207, v154 offset:1920
	ds_read_b32 v208, v154 offset:448
	ds_read_b32 v209, v154 offset:960
	ds_read_b32 v210, v154 offset:1472
	ds_read_b32 v211, v154 offset:1984
	s_waitcnt lgkmcnt(0)
	v_add_f32_e32 v160, v180, v181
	v_add_f32_e32 v160, v160, v182
	v_add_f32_e32 v160, v160, v183
	v_add_f32_e32 v161, v184, v185
	v_add_f32_e32 v161, v161, v186
	v_add_f32_e32 v161, v161, v187
	v_add_f32_e32 v162, v188, v189
	v_add_f32_e32 v162, v162, v190
	v_add_f32_e32 v162, v162, v191
	v_add_f32_e32 v163, v192, v193
	v_add_f32_e32 v163, v163, v194
	v_add_f32_e32 v163, v163, v195
	v_add_f32_e32 v164, v196, v197
	v_add_f32_e32 v164, v164, v198
	v_add_f32_e32 v164, v164, v199
	v_add_f32_e32 v165, v200, v201
	v_add_f32_e32 v165, v165, v202
	v_add_f32_e32 v165, v165, v203
	v_add_f32_e32 v166, v204, v205
	v_add_f32_e32 v166, v166, v206
	v_add_f32_e32 v166, v166, v207
	v_add_f32_e32 v167, v208, v209
	v_add_f32_e32 v167, v167, v210
	v_add_f32_e32 v167, v167, v211
	v_readlane_b32 s100, v254, 48
	v_readlane_b32 s101, v254, 49
	s_add_u32 s100, s100, 0x90000
	s_addc_u32 s101, s101, 0
	s_cmp_lg_u32 s36, 0
	s_cbranch_scc1 .Lfz_nopub
	s_mul_i32 s18, s92, 0x2400
	v_add_u32_e32 v154, s18, v152
	v_lshlrev_b32_e32 v154, 2, v154
	global_store_dword v154, v160, s[100:101] offset:0 sc1
	global_store_dword v154, v161, s[100:101] offset:64 sc1
	global_store_dword v154, v162, s[100:101] offset:128 sc1
	global_store_dword v154, v163, s[100:101] offset:192 sc1
	global_store_dword v154, v164, s[100:101] offset:512 sc1
	global_store_dword v154, v165, s[100:101] offset:576 sc1
	global_store_dword v154, v166, s[100:101] offset:640 sc1
	global_store_dword v154, v167, s[100:101] offset:704 sc1
.Lfz_nopub:
	s_waitcnt vmcnt(0)
	s_barrier
	s_mov_b64 s[20:21], exec
	v_cmp_eq_u32_e32 vcc, 0, v214
	s_and_b64 exec, exec, vcc
	s_cbranch_execz .Lfz_synced
	s_lshl_b32 s18, s95, 2
	s_add_i32 s18, s18, 0x50000
	v_mov_b32_e32 v154, s18
	v_mov_b32_e32 v155, 1
	global_atomic_add v154, v155, s[100:101]
	s_mov_b32 s19, 0
.Lfz_poll:
	s_sleep 1
	global_load_dword v155, v154, s[100:101] sc1
	s_waitcnt vmcnt(0)
	s_nop 0
	v_readfirstlane_b32 s18, v155
	s_add_i32 s19, s19, 1
	s_cmp_ge_u32 s18, 8
	s_cbranch_scc1 .Lfz_synced
	s_cmp_lt_u32 s19, 0x2000
	s_cbranch_scc1 .Lfz_poll
.Lfz_synced:
	s_mov_b64 exec, s[20:21]
	s_barrier
	v_mul_u32_u24_e32 v154, 0x4800, v129
	v_add_u32_e32 v154, v154, v152
	v_lshlrev_b32_e32 v154, 2, v154
	v_add_u32_e32 v155, 0x9000, v154
	global_load_dword v180, v154, s[100:101] offset:0 sc1
	global_load_dword v181, v155, s[100:101] offset:0 sc1
	global_load_dword v182, v154, s[100:101] offset:64 sc1
	global_load_dword v183, v155, s[100:101] offset:64 sc1
	global_load_dword v184, v154, s[100:101] offset:128 sc1
	global_load_dword v185, v155, s[100:101] offset:128 sc1
	global_load_dword v186, v154, s[100:101] offset:192 sc1
	global_load_dword v187, v155, s[100:101] offset:192 sc1
	global_load_dword v188, v154, s[100:101] offset:512 sc1
	global_load_dword v189, v155, s[100:101] offset:512 sc1
	global_load_dword v190, v154, s[100:101] offset:576 sc1
	global_load_dword v191, v155, s[100:101] offset:576 sc1
	global_load_dword v192, v154, s[100:101] offset:640 sc1
	global_load_dword v193, v155, s[100:101] offset:640 sc1
	global_load_dword v194, v154, s[100:101] offset:704 sc1
	global_load_dword v195, v155, s[100:101] offset:704 sc1
	s_waitcnt vmcnt(0)
	v_add_f32_e32 v160, v180, v181
	v_add_f32_e32 v161, v182, v183
	v_add_f32_e32 v162, v184, v185
	v_add_f32_e32 v163, v186, v187
	v_add_f32_e32 v164, v188, v189
	v_add_f32_e32 v165, v190, v191
	v_add_f32_e32 v166, v192, v193
	v_add_f32_e32 v167, v194, v195
	v_mov_b32_e32 v168, v160
	v_mov_b32_e32 v169, v161
	v_mov_b32_e32 v170, v162
	v_mov_b32_e32 v171, v163
	v_mov_b32_e32 v172, v164
	v_mov_b32_e32 v173, v165
	v_mov_b32_e32 v174, v166
	v_mov_b32_e32 v175, v167
	s_nop 1
	v_permlane32_swap_b32_e32 v160, v168
	v_permlane32_swap_b32_e32 v161, v169
	v_permlane32_swap_b32_e32 v162, v170
	v_permlane32_swap_b32_e32 v163, v171
	v_permlane32_swap_b32_e32 v164, v172
	v_permlane32_swap_b32_e32 v165, v173
	v_permlane32_swap_b32_e32 v166, v174
	v_permlane32_swap_b32_e32 v167, v175
	s_nop 1
	v_add_f32_e32 v160, v160, v168
	v_add_f32_e32 v161, v161, v169
	v_add_f32_e32 v162, v162, v170
	v_add_f32_e32 v163, v163, v171
	v_add_f32_e32 v164, v164, v172
	v_add_f32_e32 v165, v165, v173
	v_add_f32_e32 v166, v166, v174
	v_add_f32_e32 v167, v167, v175
	v_mov_b32_e32 v168, v160
	v_mov_b32_e32 v169, v161
	v_mov_b32_e32 v170, v162
	v_mov_b32_e32 v171, v163
	v_mov_b32_e32 v172, v164
	v_mov_b32_e32 v173, v165
	v_mov_b32_e32 v174, v166
	v_mov_b32_e32 v175, v167
	s_nop 1
	v_permlane16_swap_b32_e32 v160, v168
	v_permlane16_swap_b32_e32 v161, v169
	v_permlane16_swap_b32_e32 v162, v170
	v_permlane16_swap_b32_e32 v163, v171
	v_permlane16_swap_b32_e32 v164, v172
	v_permlane16_swap_b32_e32 v165, v173
	v_permlane16_swap_b32_e32 v166, v174
	v_permlane16_swap_b32_e32 v167, v175
	s_nop 1
	v_add_f32_e32 v160, v160, v168
	v_add_f32_e32 v161, v161, v169
	v_add_f32_e32 v162, v162, v170
	v_add_f32_e32 v163, v163, v171
	v_add_f32_e32 v164, v164, v172
	v_add_f32_e32 v165, v165, v173
	v_add_f32_e32 v166, v166, v174
	v_add_f32_e32 v167, v167, v175
	v_mov_b32_e32 v178, 0x358637bd
	v_mov_b32_e32 v179, 0x260
	v_fmamk_f32 v160, v160, 0x3a000000, v178
	v_mul_f32_e32 v169, 0x4f800000, v160
	v_cmp_gt_f32_e32 vcc, 0xf800000, v160
	s_nop 1
	v_cndmask_b32_e32 v168, v160, v169, vcc
	v_sqrt_f32_e32 v169, v168
	s_nop 0
	v_add_u32_e32 v170, -1, v169
	v_fma_f32 v171, -v170, v169, v168
	v_cmp_ge_f32_e64 s[18:19], 0, v171
	v_add_u32_e32 v171, 1, v169
	s_nop 0
	v_cndmask_b32_e64 v170, v169, v170, s[18:19]
	v_fma_f32 v169, -v171, v169, v168
	v_cmp_lt_f32_e64 s[18:19], 0, v169
	s_nop 1
	v_cndmask_b32_e64 v169, v170, v171, s[18:19]
	v_mul_f32_e32 v170, 0x37800000, v169
	v_cndmask_b32_e32 v169, v169, v170, vcc
	v_cmp_class_f32_e32 vcc, v168, v179
	s_nop 1
	v_cndmask_b32_e32 v168, v169, v168, vcc
	v_div_scale_f32 v169, s[18:19], v168, v168, 1.0
	v_rcp_f32_e32 v170, v169
	s_nop 1
	v_fma_f32 v171, -v169, v170, 1.0
	v_fmac_f32_e32 v170, v171, v170
	v_div_scale_f32 v171, vcc, 1.0, v168, 1.0
	v_mul_f32_e32 v172, v171, v170
	v_fma_f32 v173, -v169, v172, v171
	v_fmac_f32_e32 v172, v173, v170
	v_fma_f32 v169, -v169, v172, v171
	s_nop 0
	v_div_fmas_f32 v169, v169, v170, v172
	v_div_fixup_f32 v180, v169, v168, 1.0
	v_fmamk_f32 v161, v161, 0x3a000000, v178
	v_mul_f32_e32 v169, 0x4f800000, v161
	v_cmp_gt_f32_e32 vcc, 0xf800000, v161
	s_nop 1
	v_cndmask_b32_e32 v168, v161, v169, vcc
	v_sqrt_f32_e32 v169, v168
	s_nop 0
	v_add_u32_e32 v170, -1, v169
	v_fma_f32 v171, -v170, v169, v168
	v_cmp_ge_f32_e64 s[18:19], 0, v171
	v_add_u32_e32 v171, 1, v169
	s_nop 0
	v_cndmask_b32_e64 v170, v169, v170, s[18:19]
	v_fma_f32 v169, -v171, v169, v168
	v_cmp_lt_f32_e64 s[18:19], 0, v169
	s_nop 1
	v_cndmask_b32_e64 v169, v170, v171, s[18:19]
	v_mul_f32_e32 v170, 0x37800000, v169
	v_cndmask_b32_e32 v169, v169, v170, vcc
	v_cmp_class_f32_e32 vcc, v168, v179
	s_nop 1
	v_cndmask_b32_e32 v168, v169, v168, vcc
	v_div_scale_f32 v169, s[18:19], v168, v168, 1.0
	v_rcp_f32_e32 v170, v169
	s_nop 1
	v_fma_f32 v171, -v169, v170, 1.0
	v_fmac_f32_e32 v170, v171, v170
	v_div_scale_f32 v171, vcc, 1.0, v168, 1.0
	v_mul_f32_e32 v172, v171, v170
	v_fma_f32 v173, -v169, v172, v171
	v_fmac_f32_e32 v172, v173, v170
	v_fma_f32 v169, -v169, v172, v171
	s_nop 0
	v_div_fmas_f32 v169, v169, v170, v172
	v_div_fixup_f32 v182, v169, v168, 1.0
	v_fmamk_f32 v162, v162, 0x3a000000, v178
	v_mul_f32_e32 v169, 0x4f800000, v162
	v_cmp_gt_f32_e32 vcc, 0xf800000, v162
	s_nop 1
	v_cndmask_b32_e32 v168, v162, v169, vcc
	v_sqrt_f32_e32 v169, v168
	s_nop 0
	v_add_u32_e32 v170, -1, v169
	v_fma_f32 v171, -v170, v169, v168
	v_cmp_ge_f32_e64 s[18:19], 0, v171
	v_add_u32_e32 v171, 1, v169
	s_nop 0
	v_cndmask_b32_e64 v170, v169, v170, s[18:19]
	v_fma_f32 v169, -v171, v169, v168
	v_cmp_lt_f32_e64 s[18:19], 0, v169
	s_nop 1
	v_cndmask_b32_e64 v169, v170, v171, s[18:19]
	v_mul_f32_e32 v170, 0x37800000, v169
	v_cndmask_b32_e32 v169, v169, v170, vcc
	v_cmp_class_f32_e32 vcc, v168, v179
	s_nop 1
	v_cndmask_b32_e32 v168, v169, v168, vcc
	v_div_scale_f32 v169, s[18:19], v168, v168, 1.0
	v_rcp_f32_e32 v170, v169
	s_nop 1
	v_fma_f32 v171, -v169, v170, 1.0
	v_fmac_f32_e32 v170, v171, v170
	v_div_scale_f32 v171, vcc, 1.0, v168, 1.0
	v_mul_f32_e32 v172, v171, v170
	v_fma_f32 v173, -v169, v172, v171
	v_fmac_f32_e32 v172, v173, v170
	v_fma_f32 v169, -v169, v172, v171
	s_nop 0
	v_div_fmas_f32 v169, v169, v170, v172
	v_div_fixup_f32 v184, v169, v168, 1.0
	v_fmamk_f32 v163, v163, 0x3a000000, v178
	v_mul_f32_e32 v169, 0x4f800000, v163
	v_cmp_gt_f32_e32 vcc, 0xf800000, v163
	s_nop 1
	v_cndmask_b32_e32 v168, v163, v169, vcc
	v_sqrt_f32_e32 v169, v168
	s_nop 0
	v_add_u32_e32 v170, -1, v169
	v_fma_f32 v171, -v170, v169, v168
	v_cmp_ge_f32_e64 s[18:19], 0, v171
	v_add_u32_e32 v171, 1, v169
	s_nop 0
	v_cndmask_b32_e64 v170, v169, v170, s[18:19]
	v_fma_f32 v169, -v171, v169, v168
	v_cmp_lt_f32_e64 s[18:19], 0, v169
	s_nop 1
	v_cndmask_b32_e64 v169, v170, v171, s[18:19]
	v_mul_f32_e32 v170, 0x37800000, v169
	v_cndmask_b32_e32 v169, v169, v170, vcc
	v_cmp_class_f32_e32 vcc, v168, v179
	s_nop 1
	v_cndmask_b32_e32 v168, v169, v168, vcc
	v_div_scale_f32 v169, s[18:19], v168, v168, 1.0
	v_rcp_f32_e32 v170, v169
	s_nop 1
	v_fma_f32 v171, -v169, v170, 1.0
	v_fmac_f32_e32 v170, v171, v170
	v_div_scale_f32 v171, vcc, 1.0, v168, 1.0
	v_mul_f32_e32 v172, v171, v170
	v_fma_f32 v173, -v169, v172, v171
	v_fmac_f32_e32 v172, v173, v170
	v_fma_f32 v169, -v169, v172, v171
	s_nop 0
	v_div_fmas_f32 v169, v169, v170, v172
	v_div_fixup_f32 v186, v169, v168, 1.0
	v_fmamk_f32 v164, v164, 0x3a000000, v178
	v_mul_f32_e32 v169, 0x4f800000, v164
	v_cmp_gt_f32_e32 vcc, 0xf800000, v164
	s_nop 1
	v_cndmask_b32_e32 v168, v164, v169, vcc
	v_sqrt_f32_e32 v169, v168
	s_nop 0
	v_add_u32_e32 v170, -1, v169
	v_fma_f32 v171, -v170, v169, v168
	v_cmp_ge_f32_e64 s[18:19], 0, v171
	v_add_u32_e32 v171, 1, v169
	s_nop 0
	v_cndmask_b32_e64 v170, v169, v170, s[18:19]
	v_fma_f32 v169, -v171, v169, v168
	v_cmp_lt_f32_e64 s[18:19], 0, v169
	s_nop 1
	v_cndmask_b32_e64 v169, v170, v171, s[18:19]
	v_mul_f32_e32 v170, 0x37800000, v169
	v_cndmask_b32_e32 v169, v169, v170, vcc
	v_cmp_class_f32_e32 vcc, v168, v179
	s_nop 1
	v_cndmask_b32_e32 v168, v169, v168, vcc
	v_div_scale_f32 v169, s[18:19], v168, v168, 1.0
	v_rcp_f32_e32 v170, v169
	s_nop 1
	v_fma_f32 v171, -v169, v170, 1.0
	v_fmac_f32_e32 v170, v171, v170
	v_div_scale_f32 v171, vcc, 1.0, v168, 1.0
	v_mul_f32_e32 v172, v171, v170
	v_fma_f32 v173, -v169, v172, v171
	v_fmac_f32_e32 v172, v173, v170
	v_fma_f32 v169, -v169, v172, v171
	s_nop 0
	v_div_fmas_f32 v169, v169, v170, v172
	v_div_fixup_f32 v188, v169, v168, 1.0
	v_fmamk_f32 v165, v165, 0x3a000000, v178
	v_mul_f32_e32 v169, 0x4f800000, v165
	v_cmp_gt_f32_e32 vcc, 0xf800000, v165
	s_nop 1
	v_cndmask_b32_e32 v168, v165, v169, vcc
	v_sqrt_f32_e32 v169, v168
	s_nop 0
	v_add_u32_e32 v170, -1, v169
	v_fma_f32 v171, -v170, v169, v168
	v_cmp_ge_f32_e64 s[18:19], 0, v171
	v_add_u32_e32 v171, 1, v169
	s_nop 0
	v_cndmask_b32_e64 v170, v169, v170, s[18:19]
	v_fma_f32 v169, -v171, v169, v168
	v_cmp_lt_f32_e64 s[18:19], 0, v169
	s_nop 1
	v_cndmask_b32_e64 v169, v170, v171, s[18:19]
	v_mul_f32_e32 v170, 0x37800000, v169
	v_cndmask_b32_e32 v169, v169, v170, vcc
	v_cmp_class_f32_e32 vcc, v168, v179
	s_nop 1
	v_cndmask_b32_e32 v168, v169, v168, vcc
	v_div_scale_f32 v169, s[18:19], v168, v168, 1.0
	v_rcp_f32_e32 v170, v169
	s_nop 1
	v_fma_f32 v171, -v169, v170, 1.0
	v_fmac_f32_e32 v170, v171, v170
	v_div_scale_f32 v171, vcc, 1.0, v168, 1.0
	v_mul_f32_e32 v172, v171, v170
	v_fma_f32 v173, -v169, v172, v171
	v_fmac_f32_e32 v172, v173, v170
	v_fma_f32 v169, -v169, v172, v171
	s_nop 0
	v_div_fmas_f32 v169, v169, v170, v172
	v_div_fixup_f32 v190, v169, v168, 1.0
	v_fmamk_f32 v166, v166, 0x3a000000, v178
	v_mul_f32_e32 v169, 0x4f800000, v166
	v_cmp_gt_f32_e32 vcc, 0xf800000, v166
	s_nop 1
	v_cndmask_b32_e32 v168, v166, v169, vcc
	v_sqrt_f32_e32 v169, v168
	s_nop 0
	v_add_u32_e32 v170, -1, v169
	v_fma_f32 v171, -v170, v169, v168
	v_cmp_ge_f32_e64 s[18:19], 0, v171
	v_add_u32_e32 v171, 1, v169
	s_nop 0
	v_cndmask_b32_e64 v170, v169, v170, s[18:19]
	v_fma_f32 v169, -v171, v169, v168
	v_cmp_lt_f32_e64 s[18:19], 0, v169
	s_nop 1
	v_cndmask_b32_e64 v169, v170, v171, s[18:19]
	v_mul_f32_e32 v170, 0x37800000, v169
	v_cndmask_b32_e32 v169, v169, v170, vcc
	v_cmp_class_f32_e32 vcc, v168, v179
	s_nop 1
	v_cndmask_b32_e32 v168, v169, v168, vcc
	v_div_scale_f32 v169, s[18:19], v168, v168, 1.0
	v_rcp_f32_e32 v170, v169
	s_nop 1
	v_fma_f32 v171, -v169, v170, 1.0
	v_fmac_f32_e32 v170, v171, v170
	v_div_scale_f32 v171, vcc, 1.0, v168, 1.0
	v_mul_f32_e32 v172, v171, v170
	v_fma_f32 v173, -v169, v172, v171
	v_fmac_f32_e32 v172, v173, v170
	v_fma_f32 v169, -v169, v172, v171
	s_nop 0
	v_div_fmas_f32 v169, v169, v170, v172
	v_div_fixup_f32 v192, v169, v168, 1.0
	v_fmamk_f32 v167, v167, 0x3a000000, v178
	v_mul_f32_e32 v169, 0x4f800000, v167
	v_cmp_gt_f32_e32 vcc, 0xf800000, v167
	s_nop 1
	v_cndmask_b32_e32 v168, v167, v169, vcc
	v_sqrt_f32_e32 v169, v168
	s_nop 0
	v_add_u32_e32 v170, -1, v169
	v_fma_f32 v171, -v170, v169, v168
	v_cmp_ge_f32_e64 s[18:19], 0, v171
	v_add_u32_e32 v171, 1, v169
	s_nop 0
	v_cndmask_b32_e64 v170, v169, v170, s[18:19]
	v_fma_f32 v169, -v171, v169, v168
	v_cmp_lt_f32_e64 s[18:19], 0, v169
	s_nop 1
	v_cndmask_b32_e64 v169, v170, v171, s[18:19]
	v_mul_f32_e32 v170, 0x37800000, v169
	v_cndmask_b32_e32 v169, v169, v170, vcc
	v_cmp_class_f32_e32 vcc, v168, v179
	s_nop 1
	v_cndmask_b32_e32 v168, v169, v168, vcc
	v_div_scale_f32 v169, s[18:19], v168, v168, 1.0
	v_rcp_f32_e32 v170, v169
	s_nop 1
	v_fma_f32 v171, -v169, v170, 1.0
	v_fmac_f32_e32 v170, v171, v170
	v_div_scale_f32 v171, vcc, 1.0, v168, 1.0
	v_mul_f32_e32 v172, v171, v170
	v_fma_f32 v173, -v169, v172, v171
	v_fmac_f32_e32 v172, v173, v170
	v_fma_f32 v169, -v169, v172, v171
	s_nop 0
	v_div_fmas_f32 v169, v169, v170, v172
	v_div_fixup_f32 v194, v169, v168, 1.0
	v_readlane_b32 s18, v253, 1
	v_readlane_b32 s19, v253, 2
	s_add_u32 s18, s18, 0
	s_addc_u32 s19, s19, 0
	global_load_dwordx4 v[132:135], v153, s[18:19] offset:0
	global_load_dwordx4 v[136:139], v153, s[18:19] offset:64
	global_load_dwordx4 v[140:143], v153, s[18:19] offset:512
	global_load_dwordx4 v[244:247], v153, s[18:19] offset:576
	v_readlane_b32 s100, v253, 3
	v_readlane_b32 s101, v253, 4
	s_add_u32 s100, s100, 0
	s_addc_u32 s101, s101, 0
	s_mul_hi_i32 s18, s95, 0x38e38e39
	s_lshr_b32 s19, s18, 31
	s_ashr_i32 s18, s18, 1
	s_add_i32 s18, s18, s19
	s_add_i32 s18, s18, 1
	s_lshl_b32 s18, s18, 8
	v_subrev_u32_e32 v152, s18, v152
	s_waitcnt vmcnt(0)
	v_add_u32_e32 v154, 0, v152
	v_lshl_add_u32 v154, v154, 13, v153
	v_pk_mul_f32 v[124:125], v[124:125], v[180:181] op_sel_hi:[1,0]
	v_pk_mul_f32 v[126:127], v[126:127], v[180:181] op_sel_hi:[1,0]
	v_pk_mul_f32 v[124:125], v[124:125], v[132:133]
	v_pk_mul_f32 v[126:127], v[126:127], v[134:135]
	v_pk_mul_f32 v[120:121], v[120:121], v[180:181] op_sel_hi:[1,0]
	v_pk_mul_f32 v[122:123], v[122:123], v[180:181] op_sel_hi:[1,0]
	v_pk_mul_f32 v[120:121], v[120:121], v[136:137]
	v_pk_mul_f32 v[122:123], v[122:123], v[138:139]
	v_pk_mul_f32 v[104:105], v[104:105], v[180:181] op_sel_hi:[1,0]
	v_pk_mul_f32 v[106:107], v[106:107], v[180:181] op_sel_hi:[1,0]
	v_pk_mul_f32 v[104:105], v[104:105], v[140:141]
	v_pk_mul_f32 v[106:107], v[106:107], v[142:143]
	v_pk_mul_f32 v[96:97], v[96:97], v[180:181] op_sel_hi:[1,0]
	v_pk_mul_f32 v[98:99], v[98:99], v[180:181] op_sel_hi:[1,0]
	v_pk_mul_f32 v[96:97], v[96:97], v[244:245]
	v_pk_mul_f32 v[98:99], v[98:99], v[246:247]
	global_store_dwordx4 v154, v[124:127], s[100:101] offset:0
	global_store_dwordx4 v154, v[120:123], s[100:101] offset:64
	global_store_dwordx4 v154, v[104:107], s[100:101] offset:512
	global_store_dwordx4 v154, v[96:99], s[100:101] offset:576
	v_add_u32_e32 v154, 16, v152
	v_lshl_add_u32 v154, v154, 13, v153
	v_pk_mul_f32 v[116:117], v[116:117], v[182:183] op_sel_hi:[1,0]
	v_pk_mul_f32 v[118:119], v[118:119], v[182:183] op_sel_hi:[1,0]
	v_pk_mul_f32 v[116:117], v[116:117], v[132:133]
	v_pk_mul_f32 v[118:119], v[118:119], v[134:135]
	v_pk_mul_f32 v[112:113], v[112:113], v[182:183] op_sel_hi:[1,0]
	v_pk_mul_f32 v[114:115], v[114:115], v[182:183] op_sel_hi:[1,0]
	v_pk_mul_f32 v[112:113], v[112:113], v[136:137]
	v_pk_mul_f32 v[114:115], v[114:115], v[138:139]
	v_pk_mul_f32 v[88:89], v[88:89], v[182:183] op_sel_hi:[1,0]
	v_pk_mul_f32 v[90:91], v[90:91], v[182:183] op_sel_hi:[1,0]
	v_pk_mul_f32 v[88:89], v[88:89], v[140:141]
	v_pk_mul_f32 v[90:91], v[90:91], v[142:143]
	v_pk_mul_f32 v[84:85], v[84:85], v[182:183] op_sel_hi:[1,0]
	v_pk_mul_f32 v[86:87], v[86:87], v[182:183] op_sel_hi:[1,0]
	v_pk_mul_f32 v[84:85], v[84:85], v[244:245]
	v_pk_mul_f32 v[86:87], v[86:87], v[246:247]
	global_store_dwordx4 v154, v[116:119], s[100:101] offset:0
	global_store_dwordx4 v154, v[112:115], s[100:101] offset:64
	global_store_dwordx4 v154, v[88:91], s[100:101] offset:512
	global_store_dwordx4 v154, v[84:87], s[100:101] offset:576
	v_add_u32_e32 v154, 32, v152
	v_lshl_add_u32 v154, v154, 13, v153
	v_pk_mul_f32 v[108:109], v[108:109], v[184:185] op_sel_hi:[1,0]
	v_pk_mul_f32 v[110:111], v[110:111], v[184:185] op_sel_hi:[1,0]
	v_pk_mul_f32 v[108:109], v[108:109], v[132:133]
	v_pk_mul_f32 v[110:111], v[110:111], v[134:135]
	v_pk_mul_f32 v[100:101], v[100:101], v[184:185] op_sel_hi:[1,0]
	v_pk_mul_f32 v[102:103], v[102:103], v[184:185] op_sel_hi:[1,0]
	v_pk_mul_f32 v[100:101], v[100:101], v[136:137]
	v_pk_mul_f32 v[102:103], v[102:103], v[138:139]
	v_pk_mul_f32 v[80:81], v[80:81], v[184:185] op_sel_hi:[1,0]
	v_pk_mul_f32 v[82:83], v[82:83], v[184:185] op_sel_hi:[1,0]
	v_pk_mul_f32 v[80:81], v[80:81], v[140:141]
	v_pk_mul_f32 v[82:83], v[82:83], v[142:143]
	v_pk_mul_f32 v[76:77], v[76:77], v[184:185] op_sel_hi:[1,0]
	v_pk_mul_f32 v[78:79], v[78:79], v[184:185] op_sel_hi:[1,0]
	v_pk_mul_f32 v[76:77], v[76:77], v[244:245]
	v_pk_mul_f32 v[78:79], v[78:79], v[246:247]
	global_store_dwordx4 v154, v[108:111], s[100:101] offset:0
	global_store_dwordx4 v154, v[100:103], s[100:101] offset:64
	global_store_dwordx4 v154, v[80:83], s[100:101] offset:512
	global_store_dwordx4 v154, v[76:79], s[100:101] offset:576
	v_add_u32_e32 v154, 48, v152
	v_lshl_add_u32 v154, v154, 13, v153
	v_pk_mul_f32 v[92:93], v[92:93], v[186:187] op_sel_hi:[1,0]
	v_pk_mul_f32 v[94:95], v[94:95], v[186:187] op_sel_hi:[1,0]
	v_pk_mul_f32 v[92:93], v[92:93], v[132:133]
	v_pk_mul_f32 v[94:95], v[94:95], v[134:135]
	v_pk_mul_f32 v[72:73], v[72:73], v[186:187] op_sel_hi:[1,0]
	v_pk_mul_f32 v[74:75], v[74:75], v[186:187] op_sel_hi:[1,0]
	v_pk_mul_f32 v[72:73], v[72:73], v[136:137]
	v_pk_mul_f32 v[74:75], v[74:75], v[138:139]
	v_pk_mul_f32 v[68:69], v[68:69], v[186:187] op_sel_hi:[1,0]
	v_pk_mul_f32 v[70:71], v[70:71], v[186:187] op_sel_hi:[1,0]
	v_pk_mul_f32 v[68:69], v[68:69], v[140:141]
	v_pk_mul_f32 v[70:71], v[70:71], v[142:143]
	v_pk_mul_f32 v[64:65], v[64:65], v[186:187] op_sel_hi:[1,0]
	v_pk_mul_f32 v[66:67], v[66:67], v[186:187] op_sel_hi:[1,0]
	v_pk_mul_f32 v[64:65], v[64:65], v[244:245]
	v_pk_mul_f32 v[66:67], v[66:67], v[246:247]
	global_store_dwordx4 v154, v[92:95], s[100:101] offset:0
	global_store_dwordx4 v154, v[72:75], s[100:101] offset:64
	global_store_dwordx4 v154, v[68:71], s[100:101] offset:512
	global_store_dwordx4 v154, v[64:67], s[100:101] offset:576
	v_add_u32_e32 v154, 128, v152
	v_lshl_add_u32 v154, v154, 13, v153
	v_pk_mul_f32 v[60:61], v[60:61], v[188:189] op_sel_hi:[1,0]
	v_pk_mul_f32 v[62:63], v[62:63], v[188:189] op_sel_hi:[1,0]
	v_pk_mul_f32 v[60:61], v[60:61], v[132:133]
	v_pk_mul_f32 v[62:63], v[62:63], v[134:135]
	v_pk_mul_f32 v[56:57], v[56:57], v[188:189] op_sel_hi:[1,0]
	v_pk_mul_f32 v[58:59], v[58:59], v[188:189] op_sel_hi:[1,0]
	v_pk_mul_f32 v[56:57], v[56:57], v[136:137]
	v_pk_mul_f32 v[58:59], v[58:59], v[138:139]
	v_pk_mul_f32 v[40:41], v[40:41], v[188:189] op_sel_hi:[1,0]
	v_pk_mul_f32 v[42:43], v[42:43], v[188:189] op_sel_hi:[1,0]
	v_pk_mul_f32 v[40:41], v[40:41], v[140:141]
	v_pk_mul_f32 v[42:43], v[42:43], v[142:143]
	v_pk_mul_f32 v[36:37], v[36:37], v[188:189] op_sel_hi:[1,0]
	v_pk_mul_f32 v[38:39], v[38:39], v[188:189] op_sel_hi:[1,0]
	v_pk_mul_f32 v[36:37], v[36:37], v[244:245]
	v_pk_mul_f32 v[38:39], v[38:39], v[246:247]
	global_store_dwordx4 v154, v[60:63], s[100:101] offset:0
	global_store_dwordx4 v154, v[56:59], s[100:101] offset:64
	global_store_dwordx4 v154, v[40:43], s[100:101] offset:512
	global_store_dwordx4 v154, v[36:39], s[100:101] offset:576
	v_add_u32_e32 v154, 144, v152
	v_lshl_add_u32 v154, v154, 13, v153
	v_pk_mul_f32 v[52:53], v[52:53], v[190:191] op_sel_hi:[1,0]
	v_pk_mul_f32 v[54:55], v[54:55], v[190:191] op_sel_hi:[1,0]
	v_pk_mul_f32 v[52:53], v[52:53], v[132:133]
	v_pk_mul_f32 v[54:55], v[54:55], v[134:135]
	v_pk_mul_f32 v[48:49], v[48:49], v[190:191] op_sel_hi:[1,0]
	v_pk_mul_f32 v[50:51], v[50:51], v[190:191] op_sel_hi:[1,0]
	v_pk_mul_f32 v[48:49], v[48:49], v[136:137]
	v_pk_mul_f32 v[50:51], v[50:51], v[138:139]
	v_pk_mul_f32 v[28:29], v[28:29], v[190:191] op_sel_hi:[1,0]
	v_pk_mul_f32 v[30:31], v[30:31], v[190:191] op_sel_hi:[1,0]
	v_pk_mul_f32 v[28:29], v[28:29], v[140:141]
	v_pk_mul_f32 v[30:31], v[30:31], v[142:143]
	v_pk_mul_f32 v[24:25], v[24:25], v[190:191] op_sel_hi:[1,0]
	v_pk_mul_f32 v[26:27], v[26:27], v[190:191] op_sel_hi:[1,0]
	v_pk_mul_f32 v[24:25], v[24:25], v[244:245]
	v_pk_mul_f32 v[26:27], v[26:27], v[246:247]
	global_store_dwordx4 v154, v[52:55], s[100:101] offset:0
	global_store_dwordx4 v154, v[48:51], s[100:101] offset:64
	global_store_dwordx4 v154, v[28:31], s[100:101] offset:512
	global_store_dwordx4 v154, v[24:27], s[100:101] offset:576
	v_add_u32_e32 v154, 160, v152
	v_lshl_add_u32 v154, v154, 13, v153
	v_pk_mul_f32 v[44:45], v[44:45], v[192:193] op_sel_hi:[1,0]
	v_pk_mul_f32 v[46:47], v[46:47], v[192:193] op_sel_hi:[1,0]
	v_pk_mul_f32 v[44:45], v[44:45], v[132:133]
	v_pk_mul_f32 v[46:47], v[46:47], v[134:135]
	v_pk_mul_f32 v[32:33], v[32:33], v[192:193] op_sel_hi:[1,0]
	v_pk_mul_f32 v[34:35], v[34:35], v[192:193] op_sel_hi:[1,0]
	v_pk_mul_f32 v[32:33], v[32:33], v[136:137]
	v_pk_mul_f32 v[34:35], v[34:35], v[138:139]
	v_pk_mul_f32 v[20:21], v[20:21], v[192:193] op_sel_hi:[1,0]
	v_pk_mul_f32 v[22:23], v[22:23], v[192:193] op_sel_hi:[1,0]
	v_pk_mul_f32 v[20:21], v[20:21], v[140:141]
	v_pk_mul_f32 v[22:23], v[22:23], v[142:143]
	v_pk_mul_f32 v[12:13], v[12:13], v[192:193] op_sel_hi:[1,0]
	v_pk_mul_f32 v[14:15], v[14:15], v[192:193] op_sel_hi:[1,0]
	v_pk_mul_f32 v[12:13], v[12:13], v[244:245]
	v_pk_mul_f32 v[14:15], v[14:15], v[246:247]
	global_store_dwordx4 v154, v[44:47], s[100:101] offset:0
	global_store_dwordx4 v154, v[32:35], s[100:101] offset:64
	global_store_dwordx4 v154, v[20:23], s[100:101] offset:512
	global_store_dwordx4 v154, v[12:15], s[100:101] offset:576
	v_add_u32_e32 v154, 176, v152
	v_lshl_add_u32 v154, v154, 13, v153
	v_pk_mul_f32 v[16:17], v[16:17], v[194:195] op_sel_hi:[1,0]
	v_pk_mul_f32 v[18:19], v[18:19], v[194:195] op_sel_hi:[1,0]
	v_pk_mul_f32 v[16:17], v[16:17], v[132:133]
	v_pk_mul_f32 v[18:19], v[18:19], v[134:135]
	v_pk_mul_f32 v[8:9], v[8:9], v[194:195] op_sel_hi:[1,0]
	v_pk_mul_f32 v[10:11], v[10:11], v[194:195] op_sel_hi:[1,0]
	v_pk_mul_f32 v[8:9], v[8:9], v[136:137]
	v_pk_mul_f32 v[10:11], v[10:11], v[138:139]
	v_pk_mul_f32 v[4:5], v[4:5], v[194:195] op_sel_hi:[1,0]
	v_pk_mul_f32 v[6:7], v[6:7], v[194:195] op_sel_hi:[1,0]
	v_pk_mul_f32 v[4:5], v[4:5], v[140:141]
	v_pk_mul_f32 v[6:7], v[6:7], v[142:143]
	v_pk_mul_f32 v[0:1], v[0:1], v[194:195] op_sel_hi:[1,0]
	v_pk_mul_f32 v[2:3], v[2:3], v[194:195] op_sel_hi:[1,0]
	v_pk_mul_f32 v[0:1], v[0:1], v[244:245]
	v_pk_mul_f32 v[2:3], v[2:3], v[246:247]
	global_store_dwordx4 v154, v[16:19], s[100:101] offset:0
	global_store_dwordx4 v154, v[8:11], s[100:101] offset:64
	global_store_dwordx4 v154, v[4:7], s[100:101] offset:512
	global_store_dwordx4 v154, v[0:3], s[100:101] offset:576
	s_branch .LBB0_1807

.LBB0_1856:
	s_branch .LBB0_1859
	v_readlane_b32 s1, v253, 0
	s_lshl_b32 s1, s1, 3
	v_readfirstlane_b32 s0, v214
	s_ashr_i32 s0, s0, 6
	s_add_i32 s2, s1, s0
	v_readlane_b32 s10, v254, 38
	s_cmpk_gt_i32 s2, 0x1fff
	v_readlane_b32 s11, v254, 39
	s_cbranch_scc1 .LBB0_1859
	v_and_b32_e32 v176, 63, v214
	v_lshlrev_b32_e32 v176, 4, v176
	v_readlane_b32 s4, v253, 1
	v_readlane_b32 s5, v253, 2
	v_readlane_b32 s12, v253, 5
	s_lshl_b32 s12, s12, 3
	s_add_u32 s4, s4, 0x1000
	s_addc_u32 s5, s5, 0
	global_load_dwordx4 v[128:131], v176, s[4:5] offset:-4096
	global_load_dwordx4 v[132:135], v176, s[4:5] offset:-3072
	global_load_dwordx4 v[136:139], v176, s[4:5] offset:-2048
	global_load_dwordx4 v[140:143], v176, s[4:5] offset:-1024
	global_load_dwordx4 v[144:147], v176, s[4:5] offset:0
	global_load_dwordx4 v[148:151], v176, s[4:5] offset:1024
	global_load_dwordx4 v[152:155], v176, s[4:5] offset:2048
	global_load_dwordx4 v[156:159], v176, s[4:5] offset:3072
	s_mov_b32 s3, 0
	s_mov_b32 s13, s2
	s_cmpk_lt_i32 s13, 0x2000
	s_cbranch_scc0 .Lfin_issued
	s_lshr_b32 s6, s13, 11
	s_mul_i32 s6, s6, 0x900
	s_and_b32 s7, s13, 0x7ff
	s_add_i32 s6, s6, s7
	s_addk_i32 s6, 0x100
	s_lshl_b32 s6, s6, 13
	v_readlane_b32 s8, v253, 50
	v_readlane_b32 s9, v253, 51
	s_add_u32 s6, s6, 0x1000
	s_add_u32 s8, s8, s6
	s_addc_u32 s9, s9, 0
	global_load_dwordx4 v[0:3], v176, s[8:9] offset:-4096
	global_load_dwordx4 v[4:7], v176, s[8:9] offset:-3072
	global_load_dwordx4 v[8:11], v176, s[8:9] offset:-2048
	global_load_dwordx4 v[12:15], v176, s[8:9] offset:-1024
	global_load_dwordx4 v[16:19], v176, s[8:9] offset:0
	global_load_dwordx4 v[20:23], v176, s[8:9] offset:1024
	global_load_dwordx4 v[24:27], v176, s[8:9] offset:2048
	global_load_dwordx4 v[28:31], v176, s[8:9] offset:3072
	s_add_i32 s3, s3, 1
	s_add_i32 s13, s13, s12
	s_cmpk_lt_i32 s13, 0x2000
	s_cbranch_scc0 .Lfin_issued
	s_lshr_b32 s6, s13, 11
	s_mul_i32 s6, s6, 0x900
	s_and_b32 s7, s13, 0x7ff
	s_add_i32 s6, s6, s7
	s_addk_i32 s6, 0x100
	s_lshl_b32 s6, s6, 13
	v_readlane_b32 s8, v253, 50
	v_readlane_b32 s9, v253, 51
	s_add_u32 s6, s6, 0x1000
	s_add_u32 s8, s8, s6
	s_addc_u32 s9, s9, 0
	global_load_dwordx4 v[32:35], v176, s[8:9] offset:-4096
	global_load_dwordx4 v[36:39], v176, s[8:9] offset:-3072
	global_load_dwordx4 v[40:43], v176, s[8:9] offset:-2048
	global_load_dwordx4 v[44:47], v176, s[8:9] offset:-1024
	global_load_dwordx4 v[48:51], v176, s[8:9] offset:0
	global_load_dwordx4 v[52:55], v176, s[8:9] offset:1024
	global_load_dwordx4 v[56:59], v176, s[8:9] offset:2048
	global_load_dwordx4 v[60:63], v176, s[8:9] offset:3072
	s_add_i32 s3, s3, 1
	s_add_i32 s13, s13, s12
	s_cmpk_lt_i32 s13, 0x2000
	s_cbranch_scc0 .Lfin_issued
	s_lshr_b32 s6, s13, 11
	s_mul_i32 s6, s6, 0x900
	s_and_b32 s7, s13, 0x7ff
	s_add_i32 s6, s6, s7
	s_addk_i32 s6, 0x100
	s_lshl_b32 s6, s6, 13
	v_readlane_b32 s8, v253, 50
	v_readlane_b32 s9, v253, 51
	s_add_u32 s6, s6, 0x1000
	s_add_u32 s8, s8, s6
	s_addc_u32 s9, s9, 0
	global_load_dwordx4 v[64:67], v176, s[8:9] offset:-4096
	global_load_dwordx4 v[68:71], v176, s[8:9] offset:-3072
	global_load_dwordx4 v[72:75], v176, s[8:9] offset:-2048
	global_load_dwordx4 v[76:79], v176, s[8:9] offset:-1024
	global_load_dwordx4 v[80:83], v176, s[8:9] offset:0
	global_load_dwordx4 v[84:87], v176, s[8:9] offset:1024
	global_load_dwordx4 v[88:91], v176, s[8:9] offset:2048
	global_load_dwordx4 v[92:95], v176, s[8:9] offset:3072
	s_add_i32 s3, s3, 1
	s_add_i32 s13, s13, s12
	s_cmpk_lt_i32 s13, 0x2000
	s_cbranch_scc0 .Lfin_issued
	s_lshr_b32 s6, s13, 11
	s_mul_i32 s6, s6, 0x900
	s_and_b32 s7, s13, 0x7ff
	s_add_i32 s6, s6, s7
	s_addk_i32 s6, 0x100
	s_lshl_b32 s6, s6, 13
	v_readlane_b32 s8, v253, 50
	v_readlane_b32 s9, v253, 51
	s_add_u32 s6, s6, 0x1000
	s_add_u32 s8, s8, s6
	s_addc_u32 s9, s9, 0
	global_load_dwordx4 v[96:99], v176, s[8:9] offset:-4096
	global_load_dwordx4 v[100:103], v176, s[8:9] offset:-3072
	global_load_dwordx4 v[104:107], v176, s[8:9] offset:-2048
	global_load_dwordx4 v[108:111], v176, s[8:9] offset:-1024
	global_load_dwordx4 v[112:115], v176, s[8:9] offset:0
	global_load_dwordx4 v[116:119], v176, s[8:9] offset:1024
	global_load_dwordx4 v[120:123], v176, s[8:9] offset:2048
	global_load_dwordx4 v[124:127], v176, s[8:9] offset:3072
	s_add_i32 s3, s3, 1
	s_add_i32 s13, s13, s12
